# v17 plus: grid barrier between proj_a and proj_b GEMM phases removed (same-lane dependency only)
# speedup vs baseline: 1.0158x; 1.0012x over previous
; #define SEAM(k) do { if (IN(k) && IN((k) + 1)) { if ((k) == 0) cg::this_grid().sync(); else xcd_barrier(xbar); } } while (0)
; __device__ __forceinline__ void xcd_barrier(const XcdBarrier& b) {
;     asm volatile("s_waitcnt vmcnt(0)" ::: "memory");
;     __syncthreads();
;     if (threadIdx.x == 0) {
;         unsigned* bar = b.bar;
;         __builtin_amdgcn_s_waitcnt(0);
;         unsigned nloc = b.st[0], nx = b.st[1];
; __global__ void __launch_bounds__(512, 2) fwd_kernel(Args a) {
;     ...
;         SEAM(p0 + 2);
.LBB0_363:
	s_mul_i32 s0, s40, 10
	s_add_i32 s4, s0, 4
	s_cmp_ge_i32 s4, s65
	s_cbranch_scc1 .LBB0_413
	s_branch .LBB0_413
	s_waitcnt vmcnt(0)
	s_waitcnt vmcnt(0)
	s_barrier
	s_mov_b64 s[0:1], exec
	v_readlane_b32 s6, v252, 0
	v_readlane_b32 s7, v252, 1
	s_and_b64 s[6:7], s[0:1], s[6:7]
	s_mov_b64 exec, s[6:7]
	s_cbranch_execz .LBB0_412
	v_readlane_b32 s6, v254, 52
	s_waitcnt vmcnt(0) expcnt(0) lgkmcnt(0)
	s_nop 0
	v_mov_b32_e32 v0, s6
	ds_read_b32 v3, v0
	v_readlane_b32 s6, v254, 53
	s_waitcnt lgkmcnt(0)
	v_cmp_ne_u32_e32 vcc, 0, v3
	v_mov_b32_e32 v0, s6
	ds_read_b32 v2, v0
	s_cbranch_vccnz .LBB0_380
	v_readlane_b32 s8, v252, 2
	v_readlane_b32 s9, v252, 3
	s_load_dwordx2 s[6:7], s[8:9], 0x4
	s_mov_b32 s20, 1
	s_waitcnt lgkmcnt(0)
	s_mul_i32 s13, s6, s3
	s_mul_i32 s13, s13, s7
	s_branch .LBB0_368
